# attention Q fragment loads (read once per unit) non-temporal
# baseline (speedup 1.0000x reference)
.LBB0_126:
	s_lshl_b32 s16, s97, 8
	v_mov_b32_e32 v239, v220
	s_lshl_b32 s11, s97, 13
	s_addk_i32 s16, 0x2000
	s_cmp_gt_i32 s5, 1
	v_bfe_u32 v238, v239, 5, 1
	v_and_b32_e32 v240, 31, v239
	s_mov_b64 s[2:3], -1
	s_cbranch_scc0 .LBB0_148
	s_cmp_lt_u32 s12, 32
	v_and_b32_e32 v0, 0xffffffc0, v239
	s_cselect_b32 s13, 0, 0x80
	v_lshl_add_u32 v212, s12, 8, v0
	s_lshl_b32 s2, s97, 3
	s_add_i32 s2, s2, s96
	s_lshl_b32 s3, s97, 1
	s_ashr_i32 s8, s96, 2
	v_ashrrev_i32_e32 v213, 31, v212
	s_add_i32 s8, s8, s3
	v_mad_i64_i32 v[0:1], s[2:3], s2, v232, v[212:213]
	v_readlane_b32 s20, v252, 1
	v_mov_b32_e32 v2, v220
	v_lshlrev_b64 v[0:1], 7, v[0:1]
	v_readlane_b32 s22, v252, 3
	v_readlane_b32 s23, v252, 4
	v_readlane_b32 s24, v252, 5
	v_bfe_u32 v65, v2, 5, 1
	v_lshl_add_u64 v[0:1], s[22:23], 0, v[0:1]
	v_and_b32_e32 v66, 31, v2
	v_lshlrev_b32_e32 v192, 4, v65
	v_lshl_add_u64 v[0:1], v[0:1], 0, v[192:193]
	v_lshlrev_b32_e32 v192, 7, v66
	v_lshl_add_u64 v[0:1], v[0:1], 0, v[192:193]
	global_load_dwordx4 v[128:131], v[0:1], off nt
	global_load_dwordx4 v[132:135], v[0:1], off offset:32 nt
	global_load_dwordx4 v[136:139], v[0:1], off offset:64 nt
	global_load_dwordx4 v[140:143], v[0:1], off offset:96 nt
	v_add_co_u32_e32 v0, vcc, s6, v0
	v_bfe_u32 v5, v2, 3, 3
	s_nop 0
	v_addc_co_u32_e32 v1, vcc, 0, v1, vcc
	global_load_dwordx4 v[144:147], v[0:1], off nt
	global_load_dwordx4 v[148:151], v[0:1], off offset:32 nt
	global_load_dwordx4 v[152:155], v[0:1], off offset:64 nt
	global_load_dwordx4 v[156:159], v[0:1], off offset:96 nt
	v_ashrrev_i32_e32 v1, 6, v2
	s_mul_hi_i32 s2, s8, 0x108000
	s_mul_i32 s8, s8, 0x108000
	v_lshl_or_b32 v6, v1, 3, v5
	v_readlane_b32 s25, v252, 6
	s_add_u32 s17, s24, s8
	v_lshrrev_b32_e32 v7, 1, v6
	v_readlane_b32 s26, v252, 7
	s_addc_u32 s18, s25, s2
	v_xor_b32_e32 v7, v7, v2
	v_readlane_b32 s27, v252, 8
	s_add_u32 s19, s26, s8
	v_lshlrev_b32_e32 v7, 3, v7
	s_addc_u32 s44, s27, s2
	v_and_b32_e32 v7, 56, v7
	v_lshlrev_b32_e32 v213, 10, v1
	v_add_u32_e32 v1, 4, v1
	s_lshl_b32 s2, s13, 13
	v_lshl_or_b32 v192, v6, 6, v7
	v_mul_lo_u32 v6, v6, s4
	v_lshl_or_b32 v5, v1, 3, v5
	s_add_u32 s2, s17, s2
	v_or_b32_e32 v214, v7, v6
	v_lshrrev_b32_e32 v6, 1, v5
	s_addc_u32 s3, s18, 0
	v_lshlrev_b32_e32 v3, 1, v2
	v_lshrrev_b32_e32 v64, 1, v2
	v_and_b32_e32 v0, 19, v2
	v_xor_b32_e32 v2, v6, v2
	s_cmp_lg_u32 32, -1
	v_and_b32_e32 v3, 8, v3
	v_and_b32_e32 v4, 4, v64
	v_lshlrev_b32_e32 v2, 3, v2
	s_cselect_b32 s8, 32, 0
	v_and_b32_e32 v2, 56, v2
	v_lshlrev_b32_e32 v241, 10, v1
	v_mul_lo_u32 v1, v5, s4
	v_or3_b32 v10, v3, v0, v4
	v_add_u32_e32 v4, s8, v213
	v_or_b32_e32 v218, v2, v1
	v_lshlrev_b64 v[0:1], 1, v[192:193]
	v_readfirstlane_b32 s10, v4
	v_lshl_or_b32 v216, v5, 6, v2
	v_lshl_add_u64 v[2:3], s[2:3], 0, v[0:1]
	s_mov_b32 m0, s10
	v_mov_b32_e32 v217, v193
	global_load_lds_dwordx4 v[2:3], off
	v_lshlrev_b64 v[2:3], 1, v[216:217]
	v_add_u32_e32 v6, s8, v241
	v_lshl_add_u64 v[4:5], s[2:3], 0, v[2:3]
	v_readfirstlane_b32 s2, v6
	s_mov_b32 m0, s2
	s_lshl_b32 s2, s13, 7
	s_add_u32 s2, s19, s2
	s_addc_u32 s3, s44, 0
	s_add_i32 s10, s8, 0x2000
	v_mov_b32_e32 v215, v193
	v_add_u32_e32 v8, s10, v213
	global_load_lds_dwordx4 v[4:5], off
	v_lshlrev_b64 v[4:5], 1, v[214:215]
	v_readfirstlane_b32 s28, v8
	v_lshl_add_u64 v[6:7], s[2:3], 0, v[4:5]
	s_mov_b32 m0, s28
	v_mov_b32_e32 v219, v193
	global_load_lds_dwordx4 v[6:7], off
	v_lshlrev_b64 v[6:7], 1, v[218:219]
	v_add_u32_e32 v11, s10, v241
	v_lshl_add_u64 v[8:9], s[2:3], 0, v[6:7]
	v_readfirstlane_b32 s2, v11
	s_or_b32 s10, s13, 1
	s_mov_b32 m0, s2
	s_lshl_b32 s2, s10, 13
	s_add_u32 s2, s17, s2
	s_addc_u32 s3, s18, 0
	s_add_i32 s28, s8, 0x4000
	global_load_lds_dwordx4 v[8:9], off
	v_add_u32_e32 v8, s28, v213
	v_lshl_add_u64 v[0:1], s[2:3], 0, v[0:1]
	v_readfirstlane_b32 s29, v8
	s_mov_b32 m0, s29
	s_waitcnt vmcnt(0)
	s_waitcnt vmcnt(0) lgkmcnt(0)
	s_barrier
	global_load_lds_dwordx4 v[0:1], off
	v_lshl_add_u64 v[0:1], s[2:3], 0, v[2:3]
	v_add_u32_e32 v2, s28, v241
	v_lshrrev_b32_e32 v78, 1, v10
	v_readfirstlane_b32 s2, v2
	s_mov_b32 m0, s2
	s_lshl_b32 s2, s10, 7
	s_add_u32 s2, s19, s2
	s_addc_u32 s3, s44, 0
	s_addk_i32 s8, 0x6000
	v_add_u32_e32 v2, s8, v213
	global_load_lds_dwordx4 v[0:1], off
	v_readfirstlane_b32 s10, v2
	v_lshl_add_u64 v[0:1], s[2:3], 0, v[4:5]
	s_mov_b32 m0, s10
	v_add_u32_e32 v2, s8, v241
	global_load_lds_dwordx4 v[0:1], off
	v_lshl_add_u64 v[0:1], s[2:3], 0, v[6:7]
	v_readfirstlane_b32 s2, v2
	s_mov_b32 m0, s2
	v_lshl_add_u32 v242, v10, 7, 32
	global_load_lds_dwordx4 v[0:1], off
	v_bitop3_b32 v0, v78, v65, 7 bitop3:0x6c
	v_lshlrev_b32_e32 v243, 4, v0
	v_add_u32_e32 v4, v242, v243
	ds_read_b128 v[0:3], v4
	ds_read_b128 v[4:7], v4 offset:4096
	s_waitcnt lgkmcnt(0)
	v_mfma_f32_32x32x16_bf16 v[32:47], v[0:3], v[128:131], 0
	v_or_b32_e32 v67, 2, v65
	v_bitop3_b32 v68, v78, v67, 7 bitop3:0x6c
	v_lshlrev_b32_e32 v244, 4, v68
	v_add_u32_e32 v72, v242, v244
	ds_read_b128 v[68:71], v72
	ds_read_b128 v[72:75], v72 offset:4096
	v_readlane_b32 s21, v252, 2
	v_mfma_f32_32x32x16_bf16 v[16:31], v[0:3], v[144:147], 0
	v_mfma_f32_32x32x16_bf16 v[48:63], v[4:7], v[128:131], 0
	v_mfma_f32_32x32x16_bf16 v[0:15], v[4:7], v[144:147], 0
	s_waitcnt lgkmcnt(0)
	v_mfma_f32_32x32x16_bf16 v[32:47], v[68:71], v[132:135], v[32:47]
	v_mfma_f32_32x32x16_bf16 v[16:31], v[68:71], v[148:151], v[16:31]
	v_or_b32_e32 v68, 4, v65
	v_bitop3_b32 v69, v78, v68, 7 bitop3:0x6c
	v_lshlrev_b32_e32 v245, 4, v69
	v_add_u32_e32 v69, v242, v245
	v_mfma_f32_32x32x16_bf16 v[48:63], v[72:75], v[132:135], v[48:63]
	v_mfma_f32_32x32x16_bf16 v[0:15], v[72:75], v[148:151], v[0:15]
	ds_read_b128 v[70:73], v69
	ds_read_b128 v[74:77], v69 offset:4096
	v_or_b32_e32 v69, 6, v65
	s_waitcnt lgkmcnt(0)
	v_mfma_f32_32x32x16_bf16 v[32:47], v[70:73], v[136:139], v[32:47]
	v_mfma_f32_32x32x16_bf16 v[48:63], v[74:77], v[136:139], v[48:63]
	v_mfma_f32_32x32x16_bf16 v[16:31], v[70:73], v[152:155], v[16:31]
	v_bitop3_b32 v70, v78, v69, 7 bitop3:0x6c
	v_lshlrev_b32_e32 v246, 4, v70
	v_mfma_f32_32x32x16_bf16 v[0:15], v[74:77], v[152:155], v[0:15]
	v_add_u32_e32 v74, v242, v246
	ds_read_b128 v[70:73], v74
	ds_read_b128 v[74:77], v74 offset:4096
	s_waitcnt lgkmcnt(0)
	v_mfma_f32_32x32x16_bf16 v[32:47], v[70:73], v[140:143], v[32:47]
	v_mfma_f32_32x32x16_bf16 v[48:63], v[74:77], v[140:143], v[48:63]
	v_mfma_f32_32x32x16_bf16 v[16:31], v[70:73], v[156:159], v[16:31]
	v_mfma_f32_32x32x16_bf16 v[0:15], v[74:77], v[156:159], v[0:15]
	s_nop 9
	v_max_f32_e32 v70, v63, v63
	v_max_f32_e32 v71, v47, v47
	v_max_f32_e32 v70, v71, v70
	v_max3_f32 v71, v70, v32, v33
	v_max3_f32 v70, v70, v48, v49
	s_cmp_lg_u64 exec, 0
	v_max3_f32 v70, v70, v50, v51
	v_max3_f32 v71, v71, v34, v35
	s_cselect_b64 s[28:29], -1, 0
	v_max3_f32 v70, v70, v52, v53
	v_max3_f32 v71, v71, v36, v37
	s_cmp_eq_u64 exec, 0
	v_max3_f32 v70, v70, v54, v55
	v_max3_f32 v71, v71, v38, v39
	s_nop 0
	v_max3_f32 v70, v70, v56, v57
	v_max3_f32 v71, v71, v40, v41
	s_nop 0
	v_max3_f32 v70, v70, v58, v59
	v_max3_f32 v71, v71, v42, v43
	s_nop 0
	v_max3_f32 v70, v70, v60, v61
	v_max3_f32 v71, v71, v44, v45
	s_nop 0
	v_max3_f32 v70, v71, v70, v46
	s_nop 0
	v_max3_f32 v70, v70, v62, v70
	s_cbranch_scc1 .LBB0_129
	v_cmp_lt_i32_e32 vcc, v225, v224
	s_nop 1
	v_cndmask_b32_e32 v71, v223, v225, vcc
	v_lshlrev_b32_e32 v71, 2, v71
	ds_bpermute_b32 v71, v71, v70
	v_max_f32_e32 v70, v70, v70
	s_waitcnt lgkmcnt(0)
	v_max_f32_e32 v71, v71, v71
	v_max_f32_e32 v70, v70, v71
	v_cmp_gt_f32_e64 vcc, |v70|, s7
	s_nop 1
	v_cndmask_b32_e32 v206, 0, v70, vcc
	v_pk_add_f32 v[32:33], v[32:33], v[206:207] op_sel_hi:[1,0] neg_lo:[0,1] neg_hi:[0,1]
	v_pk_add_f32 v[48:49], v[48:49], v[206:207] op_sel_hi:[1,0] neg_lo:[0,1] neg_hi:[0,1]
	v_pk_add_f32 v[34:35], v[34:35], v[206:207] op_sel_hi:[1,0] neg_lo:[0,1] neg_hi:[0,1]
	v_pk_add_f32 v[50:51], v[50:51], v[206:207] op_sel_hi:[1,0] neg_lo:[0,1] neg_hi:[0,1]
	v_pk_add_f32 v[36:37], v[36:37], v[206:207] op_sel_hi:[1,0] neg_lo:[0,1] neg_hi:[0,1]
	v_pk_add_f32 v[52:53], v[52:53], v[206:207] op_sel_hi:[1,0] neg_lo:[0,1] neg_hi:[0,1]
	v_pk_add_f32 v[38:39], v[38:39], v[206:207] op_sel_hi:[1,0] neg_lo:[0,1] neg_hi:[0,1]
	v_pk_add_f32 v[54:55], v[54:55], v[206:207] op_sel_hi:[1,0] neg_lo:[0,1] neg_hi:[0,1]
	v_pk_add_f32 v[40:41], v[40:41], v[206:207] op_sel_hi:[1,0] neg_lo:[0,1] neg_hi:[0,1]
	v_pk_add_f32 v[56:57], v[56:57], v[206:207] op_sel_hi:[1,0] neg_lo:[0,1] neg_hi:[0,1]
	v_pk_add_f32 v[42:43], v[42:43], v[206:207] op_sel_hi:[1,0] neg_lo:[0,1] neg_hi:[0,1]
	v_pk_add_f32 v[58:59], v[58:59], v[206:207] op_sel_hi:[1,0] neg_lo:[0,1] neg_hi:[0,1]
	v_pk_add_f32 v[44:45], v[44:45], v[206:207] op_sel_hi:[1,0] neg_lo:[0,1] neg_hi:[0,1]
	v_pk_add_f32 v[60:61], v[60:61], v[206:207] op_sel_hi:[1,0] neg_lo:[0,1] neg_hi:[0,1]
	v_pk_add_f32 v[46:47], v[46:47], v[206:207] op_sel_hi:[1,0] neg_lo:[0,1] neg_hi:[0,1]
	v_pk_add_f32 v[62:63], v[62:63], v[206:207] op_sel_hi:[1,0] neg_lo:[0,1] neg_hi:[0,1]
	s_branch .LBB0_130

.LBB0_148:
	s_and_b64 vcc, exec, s[2:3]
	s_cbranch_vccz .LBB0_99
	v_ashrrev_i32_e32 v0, 1, v239
	v_and_b32_e32 v0, 0xffffffe0, v0
	v_lshl_add_u32 v138, s12, 7, v0
	v_or_b32_e32 v0, v138, v240
	v_mov_b32_e32 v1, s16
	v_mov_b32_e32 v2, s11
	v_cmp_gt_i32_e32 vcc, s33, v0
	s_lshl_b32 s2, s12, 1
	s_and_b32 s13, s2, 0x80
	v_cndmask_b32_e32 v1, v1, v2, vcc
	v_add_u32_e32 v0, v1, v0
	v_ashrrev_i32_e32 v1, 31, v0
	v_lshlrev_b64 v[0:1], 11, v[0:1]
	v_lshl_add_u64 v[136:137], s[74:75], 0, v[0:1]
	s_cmp_lg_u32 s5, 0
	v_ashrrev_i32_e32 v139, 31, v138
	s_cbranch_scc0 .LBB0_152
	s_lshl_b32 s2, s97, 3
	s_lshl_b32 s18, s96, 1
	s_add_i32 s18, s18, s2
	v_mad_i64_i32 v[0:1], s[2:3], s18, v232, v[138:139]
	v_lshlrev_b64 v[0:1], 6, v[0:1]
	v_lshl_add_u64 v[2:3], s[84:85], 0, v[0:1]
	v_mov_b32_e32 v1, v220
	s_mul_i32 s3, s18, 0x84000
	v_and_b32_e32 v0, 31, v1
	v_bfe_u32 v58, v1, 5, 1
	v_lshlrev_b32_e32 v192, 6, v0
	v_lshl_add_u64 v[2:3], v[2:3], 0, v[192:193]
	v_lshlrev_b32_e32 v192, 4, v58
	v_lshl_add_u64 v[2:3], v[2:3], 0, v[192:193]
	global_load_dwordx4 v[100:103], v[2:3], off nt
	v_lshrrev_b32_e32 v9, 4, v1
	s_mul_hi_i32 s2, s18, 0x84000
	s_add_u32 s50, s86, s3
	v_xor_b32_e32 v9, v9, v1
	s_addc_u32 s51, s87, s2
	s_lshl_b32 s2, s97, 2
	global_load_dwordx4 v[96:99], v[2:3], off offset:32 nt
	v_ashrrev_i32_e32 v3, 6, v1
	v_lshlrev_b32_e32 v8, 3, v1
	v_lshlrev_b32_e32 v9, 3, v9
	s_add_i32 s2, s2, s96
	v_bfe_u32 v6, v1, 3, 3
	v_lshlrev_b32_e32 v7, 9, v3
	v_and_b32_e32 v8, 0x1e0, v8
	v_and_b32_e32 v9, 24, v9
	s_mul_hi_i32 s3, s2, 0x108000
	s_mul_i32 s2, s2, 0x108000
	v_readlane_b32 s20, v252, 1
	v_or3_b32 v192, v8, v7, v9
	v_lshl_or_b32 v7, v3, 3, v6
	v_readlane_b32 s21, v252, 2
	s_add_u32 s19, s20, s2
	v_mul_lo_u32 v8, v7, s4
	v_lshrrev_b32_e32 v7, 1, v7
	s_addc_u32 s5, s21, s3
	v_lshlrev_b32_e32 v109, 10, v3
	v_xor_b32_e32 v7, v7, v1
	v_add_u32_e32 v3, 4, v3
	s_lshl_b32 s2, s13, 12
	v_lshlrev_b32_e32 v7, 3, v7
	v_lshl_or_b32 v6, v3, 3, v6
	s_add_u32 s2, s50, s2
	v_and_or_b32 v104, v7, 56, v8
	v_mul_lo_u32 v7, v6, s4
	v_lshrrev_b32_e32 v6, 1, v6
	s_addc_u32 s3, s51, 0
	v_lshlrev_b32_e32 v4, 1, v1
	v_lshrrev_b32_e32 v16, 1, v1
	v_and_b32_e32 v2, 19, v1
	v_xor_b32_e32 v1, v6, v1
	s_cmp_lg_u32 32, -1
	v_and_b32_e32 v4, 8, v4
	v_and_b32_e32 v5, 4, v16
	v_lshlrev_b32_e32 v1, 3, v1
	s_cselect_b32 s8, 32, 0
	v_and_or_b32 v106, v1, 56, v7
	v_or3_b32 v1, v4, v2, v5
	v_lshlrev_b64 v[14:15], 1, v[192:193]
	v_add_u32_e32 v4, s8, v109
	v_lshlrev_b32_e32 v113, 10, v3
	v_lshl_add_u64 v[2:3], s[2:3], 0, v[14:15]
	v_readfirstlane_b32 s2, v4
	s_mov_b32 m0, s2
	s_lshl_b32 s2, s13, 7
	s_add_u32 s46, s19, s2
	s_addc_u32 s47, s5, 0
	s_add_i32 s2, s8, 0x1000
	v_mov_b32_e32 v105, v193
	v_add_u32_e32 v6, s2, v109
	v_lshlrev_b64 v[22:23], 1, v[104:105]
	v_readfirstlane_b32 s3, v6
	v_add_u32_e32 v8, s2, v113
	global_load_lds_dwordx4 v[2:3], off
	v_lshl_add_u64 v[4:5], s[46:47], 0, v[22:23]
	s_mov_b32 m0, s3
	v_readfirstlane_b32 s2, v8
	global_load_lds_dwordx4 v[4:5], off
	v_mov_b32_e32 v107, v193
	s_mov_b32 m0, s2
	s_add_i32 s2, s8, 0x3000
	v_lshlrev_b64 v[24:25], 1, v[106:107]
	v_add_u32_e32 v8, s2, v109
	v_lshl_add_u64 v[6:7], s[46:47], 0, v[24:25]
	v_readfirstlane_b32 s2, v8
	global_load_lds_dwordx4 v[6:7], off
	v_lshl_add_u64 v[2:3], v[2:3], 0, s[34:35]
	s_mov_b32 m0, s2
	s_add_i32 s2, s8, 0x4000
	global_load_lds_dwordx4 v[2:3], off
	v_lshl_add_u64 v[2:3], v[4:5], 0, s[36:37]
	v_add_u32_e32 v4, s2, v109
	v_lshrrev_b32_e32 v10, 2, v1
	v_readfirstlane_b32 s3, v4
	v_add_u32_e32 v4, s2, v113
	s_mov_b32 m0, s3
	v_readfirstlane_b32 s2, v4
	global_load_lds_dwordx4 v[2:3], off
	v_lshl_add_u64 v[2:3], v[6:7], 0, s[36:37]
	s_mov_b32 m0, s2
	v_lshlrev_b32_e32 v115, 6, v1
	global_load_lds_dwordx4 v[2:3], off
	v_bitop3_b32 v2, v10, v58, 3 bitop3:0x6c
	v_add_u32_e32 v1, 32, v115
	v_lshlrev_b32_e32 v116, 4, v2
	v_add_u32_e32 v119, v1, v116
	s_waitcnt vmcnt(0)
	s_waitcnt vmcnt(0) lgkmcnt(0)
	s_barrier
	ds_read_b128 v[2:5], v119
	v_or_b32_e32 v17, 2, v58
	s_or_b32 s10, s13, 2
	v_bitop3_b32 v10, v10, v17, 3 bitop3:0x6c
	s_lshl_b32 s17, s10, 12
	v_lshlrev_b32_e32 v117, 4, v10
	s_add_u32 s2, s50, s17
	v_add_u32_e32 v111, v1, v117
	s_addc_u32 s3, s51, 0
	ds_read_b128 v[6:9], v119 offset:2048
	ds_read_b128 v[10:13], v111
	ds_read_b128 v[18:21], v111 offset:2048
	s_waitcnt lgkmcnt(3)
	v_mfma_f32_32x32x16_bf16 v[42:57], v[2:5], v[100:103], 0
	v_lshl_add_u64 v[2:3], s[2:3], 0, v[14:15]
	s_add_i32 s2, s8, 0x6000
	v_add_u32_e32 v1, s2, v109
	v_cmp_lt_i32_e32 vcc, v225, v224
	v_readfirstlane_b32 s2, v1
	s_mov_b32 m0, s2
	s_lshl_b32 s2, s10, 7
	s_add_u32 s48, s19, s2
	s_addc_u32 s49, s5, 0
	s_addk_i32 s8, 0x7000
	v_add_u32_e32 v1, s8, v109
	global_load_lds_dwordx4 v[2:3], off
	v_readfirstlane_b32 s2, v1
	v_add_u32_e32 v1, s8, v113
	v_lshl_add_u64 v[2:3], s[48:49], 0, v[22:23]
	s_mov_b32 m0, s2
	v_readfirstlane_b32 s2, v1
	global_load_lds_dwordx4 v[2:3], off
	v_lshl_add_u64 v[2:3], s[48:49], 0, v[24:25]
	s_mov_b32 m0, s2
	s_waitcnt lgkmcnt(0)
	v_mfma_f32_32x32x16_bf16 v[26:41], v[6:9], v[100:103], 0
	global_load_lds_dwordx4 v[2:3], off
	ds_read_b128 v[2:5], v119 offset:12288
	ds_read_b128 v[6:9], v111 offset:14336
	v_readlane_b32 s22, v252, 3
	v_readlane_b32 s23, v252, 4
	v_readlane_b32 s24, v252, 5
	s_waitcnt lgkmcnt(0)
	v_mfma_f32_32x32x16_bf16 v[64:79], v[2:5], v[100:103], 0
	ds_read_b128 v[2:5], v119 offset:14336
	v_readlane_b32 s25, v252, 6
	v_readlane_b32 s26, v252, 7
	v_readlane_b32 s27, v252, 8
	s_waitcnt lgkmcnt(0)
	v_mfma_f32_32x32x16_bf16 v[80:95], v[2:5], v[100:103], 0
	ds_read_b128 v[2:5], v111 offset:12288
	v_mfma_f32_32x32x16_bf16 v[42:57], v[10:13], v[96:99], v[42:57]
	v_mfma_f32_32x32x16_bf16 v[26:41], v[18:21], v[96:99], v[26:41]
	s_waitcnt lgkmcnt(0)
	v_mfma_f32_32x32x16_bf16 v[64:79], v[2:5], v[96:99], v[64:79]
	s_nop 9
	v_max_f32_e32 v1, v41, v41
	v_max_f32_e32 v2, v57, v57
	v_max_f32_e32 v1, v2, v1
	v_max3_f32 v2, v1, v42, v43
	v_max3_f32 v1, v1, v26, v27
	s_nop 0
	v_max3_f32 v2, v2, v44, v45
	v_max3_f32 v1, v1, v28, v29
	v_mfma_f32_32x32x16_bf16 v[80:95], v[6:9], v[96:99], v[80:95]
	v_max3_f32 v2, v2, v46, v47
	v_max3_f32 v1, v1, v30, v31
	s_nop 0
	v_max3_f32 v2, v2, v48, v49
	v_max3_f32 v1, v1, v32, v33
	s_nop 0
	v_max3_f32 v2, v2, v50, v51
	v_max3_f32 v1, v1, v34, v35
	s_nop 0
	v_max3_f32 v2, v2, v52, v53
	v_max3_f32 v1, v1, v36, v37
	s_nop 0
	v_max3_f32 v2, v2, v54, v55
	v_max3_f32 v1, v1, v38, v39
	s_nop 0
	v_max3_f32 v1, v2, v1, v56
	v_cndmask_b32_e32 v2, v223, v225, vcc
	v_lshlrev_b32_e32 v178, 2, v2
	v_max3_f32 v1, v1, v40, v1
	ds_bpermute_b32 v2, v178, v1
	v_max_f32_e32 v1, v1, v1
	s_waitcnt lgkmcnt(0)
	v_max_f32_e32 v2, v2, v2
	v_max_f32_e32 v1, v1, v2
	v_cmp_gt_f32_e64 vcc, |v1|, s7
	s_cmp_lg_u64 vcc, 0
	s_cselect_b64 s[28:29], -1, 0
	s_cmp_eq_u64 vcc, 0
	s_cselect_b64 s[42:43], -1, 0
	s_cbranch_vccz .LBB0_153
	v_cndmask_b32_e32 v108, 0, v1, vcc
	v_pk_add_f32 v[42:43], v[42:43], v[108:109] op_sel_hi:[1,0] neg_lo:[0,1] neg_hi:[0,1]
	v_pk_add_f32 v[26:27], v[26:27], v[108:109] op_sel_hi:[1,0] neg_lo:[0,1] neg_hi:[0,1]
	v_pk_add_f32 v[44:45], v[44:45], v[108:109] op_sel_hi:[1,0] neg_lo:[0,1] neg_hi:[0,1]
	v_pk_add_f32 v[28:29], v[28:29], v[108:109] op_sel_hi:[1,0] neg_lo:[0,1] neg_hi:[0,1]
	v_pk_add_f32 v[46:47], v[46:47], v[108:109] op_sel_hi:[1,0] neg_lo:[0,1] neg_hi:[0,1]
	v_pk_add_f32 v[30:31], v[30:31], v[108:109] op_sel_hi:[1,0] neg_lo:[0,1] neg_hi:[0,1]
	v_pk_add_f32 v[48:49], v[48:49], v[108:109] op_sel_hi:[1,0] neg_lo:[0,1] neg_hi:[0,1]
	v_pk_add_f32 v[32:33], v[32:33], v[108:109] op_sel_hi:[1,0] neg_lo:[0,1] neg_hi:[0,1]
	v_pk_add_f32 v[50:51], v[50:51], v[108:109] op_sel_hi:[1,0] neg_lo:[0,1] neg_hi:[0,1]
	v_pk_add_f32 v[34:35], v[34:35], v[108:109] op_sel_hi:[1,0] neg_lo:[0,1] neg_hi:[0,1]
	v_pk_add_f32 v[52:53], v[52:53], v[108:109] op_sel_hi:[1,0] neg_lo:[0,1] neg_hi:[0,1]
	v_pk_add_f32 v[36:37], v[36:37], v[108:109] op_sel_hi:[1,0] neg_lo:[0,1] neg_hi:[0,1]
	v_pk_add_f32 v[54:55], v[54:55], v[108:109] op_sel_hi:[1,0] neg_lo:[0,1] neg_hi:[0,1]
	v_pk_add_f32 v[38:39], v[38:39], v[108:109] op_sel_hi:[1,0] neg_lo:[0,1] neg_hi:[0,1]
	v_pk_add_f32 v[56:57], v[56:57], v[108:109] op_sel_hi:[1,0] neg_lo:[0,1] neg_hi:[0,1]
	v_pk_add_f32 v[40:41], v[40:41], v[108:109] op_sel_hi:[1,0] neg_lo:[0,1] neg_hi:[0,1]
	v_sub_f32_e32 v79, v79, v108
	v_sub_f32_e32 v78, v78, v108
	v_sub_f32_e32 v77, v77, v108
	v_sub_f32_e32 v76, v76, v108
	v_sub_f32_e32 v75, v75, v108
	v_sub_f32_e32 v74, v74, v108
	v_sub_f32_e32 v73, v73, v108
	v_sub_f32_e32 v72, v72, v108
	v_sub_f32_e32 v71, v71, v108
	v_sub_f32_e32 v70, v70, v108
	v_sub_f32_e32 v69, v69, v108
	v_sub_f32_e32 v68, v68, v108
	v_sub_f32_e32 v67, v67, v108
	v_sub_f32_e32 v66, v66, v108
	v_sub_f32_e32 v65, v65, v108
	v_sub_f32_e32 v64, v64, v108
	v_sub_f32_e32 v95, v95, v108
	v_sub_f32_e32 v94, v94, v108
	v_sub_f32_e32 v93, v93, v108
	v_sub_f32_e32 v92, v92, v108
	v_sub_f32_e32 v91, v91, v108
	v_sub_f32_e32 v90, v90, v108
	v_sub_f32_e32 v89, v89, v108
	v_sub_f32_e32 v88, v88, v108
	v_sub_f32_e32 v87, v87, v108
	v_sub_f32_e32 v86, v86, v108
	v_sub_f32_e32 v85, v85, v108
	v_sub_f32_e32 v84, v84, v108
	v_sub_f32_e32 v83, v83, v108
	v_sub_f32_e32 v82, v82, v108
	v_sub_f32_e32 v81, v81, v108
	v_sub_f32_e32 v80, v80, v108
	s_branch .LBB0_154

.LBB0_182:
	s_add_u32 s28, s18, 0x2100
	s_addc_u32 s29, s68, 0
	s_add_i32 s2, s12, 32
	v_add_u32_e32 v96, s2, v112
	v_add_u32_e32 v98, v96, v114
	v_exp_f32_e32 v101, v48
	v_exp_f32_e32 v103, v49
	v_exp_f32_e32 v105, v50
	v_exp_f32_e32 v107, v51
	ds_read_b128 v[48:51], v98 offset:4096
	ds_read_b128 v[130:133], v98 offset:8192
	v_exp_f32_e32 v109, v52
	v_exp_f32_e32 v97, v53
	v_exp_f32_e32 v99, v54
	v_exp_f32_e32 v113, v55
	v_add_u32_e32 v98, v96, v124
	v_cvt_pk_bf16_f32 v52, v101, v103
	v_cvt_pk_bf16_f32 v53, v105, v107
	v_cvt_pk_bf16_f32 v54, v109, v97
	v_cvt_pk_bf16_f32 v55, v99, v113
	ds_read_b128 v[140:143], v98 offset:4096
	ds_read_b128 v[156:159], v98 offset:8192
	s_waitcnt lgkmcnt(3)
	v_mfma_f32_32x32x16_bf16 v[0:15], v[48:51], v[52:55], v[0:15]
	v_exp_f32_e32 v123, v56
	v_exp_f32_e32 v121, v57
	v_exp_f32_e32 v119, v58
	v_exp_f32_e32 v117, v59
	v_exp_f32_e32 v115, v60
	v_exp_f32_e32 v149, v61
	v_exp_f32_e32 v147, v62
	s_waitcnt lgkmcnt(2)
	v_mfma_f32_32x32x16_bf16 v[16:31], v[130:133], v[52:55], v[16:31]
	v_exp_f32_e32 v145, v63
	v_cvt_pk_bf16_f32 v54, v123, v121
	v_cvt_pk_bf16_f32 v55, v119, v117
	v_cvt_pk_bf16_f32 v56, v115, v149
	v_cvt_pk_bf16_f32 v57, v147, v145
	v_add_u32_e32 v48, v96, v128
	v_exp_f32_e32 v49, v32
	s_waitcnt lgkmcnt(1)
	v_mfma_f32_32x32x16_bf16 v[0:15], v[140:143], v[54:57], v[0:15]
	v_exp_f32_e32 v53, v33
	v_exp_f32_e32 v51, v34
	v_exp_f32_e32 v155, v35
	v_exp_f32_e32 v153, v36
	v_exp_f32_e32 v127, v37
	v_exp_f32_e32 v125, v38
	v_exp_f32_e32 v111, v39
	s_waitcnt lgkmcnt(0)
	v_mfma_f32_32x32x16_bf16 v[16:31], v[156:159], v[54:57], v[16:31]
	ds_read_b128 v[32:35], v48 offset:4096
	ds_read_b128 v[54:57], v48 offset:8192
	v_add_u32_e32 v48, v96, v129
	v_cvt_pk_bf16_f32 v36, v49, v53
	v_cvt_pk_bf16_f32 v37, v51, v155
	v_cvt_pk_bf16_f32 v38, v153, v127
	v_cvt_pk_bf16_f32 v39, v125, v111
	ds_read_b128 v[58:61], v48 offset:4096
	ds_read_b128 v[130:133], v48 offset:8192
	s_waitcnt lgkmcnt(3)
	v_mfma_f32_32x32x16_bf16 v[0:15], v[32:35], v[36:39], v[0:15]
	v_exp_f32_e32 v169, v40
	v_exp_f32_e32 v167, v41
	v_exp_f32_e32 v165, v42
	v_exp_f32_e32 v159, v43
	v_exp_f32_e32 v157, v44
	v_exp_f32_e32 v163, v45
	v_exp_f32_e32 v161, v46
	s_waitcnt lgkmcnt(2)
	v_mfma_f32_32x32x16_bf16 v[16:31], v[54:57], v[36:39], v[16:31]
	v_exp_f32_e32 v151, v47
	v_add_u32_e32 v44, s10, v112
	v_cvt_pk_bf16_f32 v32, v169, v167
	v_cvt_pk_bf16_f32 v33, v165, v159
	v_cvt_pk_bf16_f32 v34, v157, v163
	v_cvt_pk_bf16_f32 v35, v161, v151
	v_add_u32_e32 v40, v44, v114
	s_waitcnt vmcnt(0)
	s_waitcnt lgkmcnt(0)
	v_mfma_f32_32x32x16_bf16 v[0:15], v[58:61], v[32:35], v[0:15]
	s_barrier
	v_exp_f32_e32 v100, v80
	v_exp_f32_e32 v102, v81
	v_exp_f32_e32 v104, v82
	v_exp_f32_e32 v106, v83
	v_exp_f32_e32 v108, v84
	v_mfma_f32_32x32x16_bf16 v[16:31], v[130:133], v[32:35], v[16:31]
	ds_read_b128 v[32:35], v40 offset:4096
	v_exp_f32_e32 v96, v85
	v_exp_f32_e32 v98, v86
	v_exp_f32_e32 v112, v87
	v_cvt_pk_bf16_f32 v36, v100, v102
	v_cvt_pk_bf16_f32 v37, v104, v106
	v_cvt_pk_bf16_f32 v38, v108, v96
	v_cvt_pk_bf16_f32 v39, v98, v112
	ds_read_b128 v[40:43], v40 offset:8192
	v_add_u32_e32 v45, v44, v124
	s_waitcnt lgkmcnt(1)
	v_mfma_f32_32x32x16_bf16 v[0:15], v[32:35], v[36:39], v[0:15]
	ds_read_b128 v[32:35], v45 offset:4096
	v_exp_f32_e32 v122, v88
	v_exp_f32_e32 v120, v89
	v_exp_f32_e32 v118, v90
	v_exp_f32_e32 v116, v91
	v_exp_f32_e32 v114, v92
	v_exp_f32_e32 v148, v93
	v_exp_f32_e32 v146, v94
	v_exp_f32_e32 v144, v95
	s_waitcnt lgkmcnt(1)
	v_mfma_f32_32x32x16_bf16 v[16:31], v[40:43], v[36:39], v[16:31]
	v_cvt_pk_bf16_f32 v36, v122, v120
	v_cvt_pk_bf16_f32 v37, v118, v116
	v_cvt_pk_bf16_f32 v38, v114, v148
	v_cvt_pk_bf16_f32 v39, v146, v144
	ds_read_b128 v[40:43], v45 offset:8192
	v_add_u32_e32 v45, v44, v128
	v_exp_f32_e32 v48, v64
	s_waitcnt lgkmcnt(1)
	v_mfma_f32_32x32x16_bf16 v[0:15], v[32:35], v[36:39], v[0:15]
	ds_read_b128 v[32:35], v45 offset:4096
	v_exp_f32_e32 v52, v65
	v_exp_f32_e32 v50, v66
	v_exp_f32_e32 v154, v67
	v_exp_f32_e32 v152, v68
	v_exp_f32_e32 v126, v69
	v_exp_f32_e32 v124, v70
	v_exp_f32_e32 v110, v71
	s_waitcnt lgkmcnt(1)
	v_mfma_f32_32x32x16_bf16 v[16:31], v[40:43], v[36:39], v[16:31]
	v_cvt_pk_bf16_f32 v36, v48, v52
	v_cvt_pk_bf16_f32 v37, v50, v154
	v_cvt_pk_bf16_f32 v38, v152, v126
	v_cvt_pk_bf16_f32 v39, v124, v110
	ds_read_b128 v[40:43], v45 offset:8192
	v_add_u32_e32 v44, v44, v129
	v_exp_f32_e32 v168, v72
	s_waitcnt lgkmcnt(1)
	v_mfma_f32_32x32x16_bf16 v[0:15], v[32:35], v[36:39], v[0:15]
	ds_read_b128 v[32:35], v44 offset:4096
	v_exp_f32_e32 v166, v73
	v_exp_f32_e32 v164, v74
	v_exp_f32_e32 v158, v75
	v_exp_f32_e32 v156, v76
	v_exp_f32_e32 v162, v77
	v_exp_f32_e32 v160, v78
	v_exp_f32_e32 v150, v79
	s_waitcnt lgkmcnt(1)
	v_mfma_f32_32x32x16_bf16 v[16:31], v[40:43], v[36:39], v[16:31]
	v_cvt_pk_bf16_f32 v36, v168, v166
	v_cvt_pk_bf16_f32 v37, v164, v158
	v_cvt_pk_bf16_f32 v38, v156, v162
	v_cvt_pk_bf16_f32 v39, v160, v150
	s_lshl_b64 s[2:3], s[28:29], 6
	s_add_u32 s50, s86, s2
	s_addc_u32 s51, s87, s3
	s_waitcnt lgkmcnt(0)
	v_mfma_f32_32x32x16_bf16 v[0:15], v[32:35], v[36:39], v[0:15]
	ds_read_b128 v[32:35], v44 offset:8192
	s_waitcnt vmcnt(0)
	s_waitcnt lgkmcnt(0)
	s_barrier
	s_lshl_b32 s2, s8, 1
	s_add_u32 s2, s50, s2
	v_mfma_f32_32x32x16_bf16 v[16:31], v[32:35], v[36:39], v[16:31]
	v_lshl_add_u64 v[32:33], s[28:29], 0, v[138:139]
	v_mov_b32_e32 v34, v220
	v_lshlrev_b64 v[32:33], 6, v[32:33]
	v_lshl_add_u64 v[32:33], s[84:85], 0, v[32:33]
	v_and_b32_e32 v64, 31, v34
	v_bfe_u32 v72, v34, 5, 1
	v_lshlrev_b32_e32 v192, 6, v64
	v_lshl_add_u64 v[32:33], v[32:33], 0, v[192:193]
	v_lshlrev_b32_e32 v192, 4, v72
	v_lshl_add_u64 v[32:33], v[32:33], 0, v[192:193]
	global_load_dwordx4 v[132:135], v[32:33], off nt
	global_load_dwordx4 v[128:131], v[32:33], off offset:32 nt
	v_lshrrev_b32_e32 v40, 4, v34
	v_xor_b32_e32 v40, v40, v34
	v_ashrrev_i32_e32 v33, 6, v34
	v_lshlrev_b32_e32 v39, 3, v34
	v_lshlrev_b32_e32 v40, 3, v40
	v_bfe_u32 v37, v34, 3, 3
	v_lshlrev_b32_e32 v38, 9, v33
	v_and_b32_e32 v39, 0x1e0, v39
	v_and_b32_e32 v40, 24, v40
	v_or3_b32 v192, v39, v38, v40
	v_lshl_or_b32 v38, v33, 3, v37
	v_mul_lo_u32 v39, v38, s4
	v_lshrrev_b32_e32 v38, 1, v38
	v_lshlrev_b32_e32 v170, 10, v33
	v_xor_b32_e32 v38, v38, v34
	v_add_u32_e32 v33, 4, v33
	v_lshlrev_b32_e32 v38, 3, v38
	v_lshl_or_b32 v37, v33, 3, v37
	v_and_or_b32 v140, v38, 56, v39
	v_mul_lo_u32 v38, v37, s4
	v_lshrrev_b32_e32 v37, 1, v37
	s_addc_u32 s3, s51, 0
	v_lshlrev_b32_e32 v35, 1, v34
	v_lshrrev_b32_e32 v73, 1, v34
	v_and_b32_e32 v32, 19, v34
	v_xor_b32_e32 v34, v37, v34
	s_cmp_lg_u32 32, -1
	v_lshlrev_b32_e32 v34, 3, v34
	s_cselect_b32 s8, 32, 0
	v_and_b32_e32 v35, 8, v35
	v_and_b32_e32 v36, 4, v73
	v_and_or_b32 v142, v34, 56, v38
	v_lshlrev_b64 v[58:59], 1, v[192:193]
	v_add_u32_e32 v34, s8, v170
	v_lshlrev_b32_e32 v171, 10, v33
	v_or3_b32 v38, v35, v32, v36
	v_lshl_add_u64 v[32:33], s[2:3], 0, v[58:59]
	v_readfirstlane_b32 s2, v34
	s_mov_b32 m0, s2
	s_add_i32 s2, s8, 0x1000
	v_mov_b32_e32 v141, v193
	v_add_u32_e32 v36, s2, v170
	v_lshlrev_b64 v[60:61], 1, v[140:141]
	v_readfirstlane_b32 s3, v36
	v_add_u32_e32 v39, s2, v171
	global_load_lds_dwordx4 v[32:33], off
	v_lshl_add_u64 v[34:35], s[46:47], 0, v[60:61]
	s_mov_b32 m0, s3
	v_readfirstlane_b32 s2, v39
	global_load_lds_dwordx4 v[34:35], off
	v_mov_b32_e32 v143, v193
	s_mov_b32 m0, s2
	s_add_i32 s2, s8, 0x3000
	v_lshlrev_b64 v[62:63], 1, v[142:143]
	v_add_u32_e32 v39, s2, v170
	v_lshl_add_u64 v[36:37], s[46:47], 0, v[62:63]
	v_readfirstlane_b32 s2, v39
	global_load_lds_dwordx4 v[36:37], off
	v_lshl_add_u64 v[32:33], v[32:33], 0, s[34:35]
	s_mov_b32 m0, s2
	s_add_i32 s2, s8, 0x4000
	global_load_lds_dwordx4 v[32:33], off
	v_lshl_add_u64 v[32:33], v[34:35], 0, s[36:37]
	v_add_u32_e32 v34, s2, v170
	v_lshrrev_b32_e32 v65, 2, v38
	v_readfirstlane_b32 s3, v34
	v_add_u32_e32 v34, s2, v171
	s_mov_b32 m0, s3
	v_readfirstlane_b32 s2, v34
	global_load_lds_dwordx4 v[32:33], off
	s_mov_b32 m0, s2
	s_add_u32 s2, s50, s17
	v_lshl_add_u64 v[32:33], v[36:37], 0, s[36:37]
	v_or_b32_e32 v74, 2, v72
	s_addc_u32 s3, s51, 0
	global_load_lds_dwordx4 v[32:33], off
	v_bitop3_b32 v32, v65, v72, 3 bitop3:0x6c
	v_bitop3_b32 v65, v65, v74, 3 bitop3:0x6c
	v_lshl_add_u64 v[58:59], s[2:3], 0, v[58:59]
	s_add_i32 s2, s8, 0x6000
	v_lshlrev_b32_e32 v172, 6, v38
	v_lshlrev_b32_e32 v174, 4, v65
	v_add_u32_e32 v65, s2, v170
	v_add_u32_e32 v66, 32, v172
	v_lshlrev_b32_e32 v173, 4, v32
	v_readfirstlane_b32 s2, v65
	v_add_u32_e32 v177, v66, v173
	v_add_u32_e32 v176, v66, v174
	s_mov_b32 m0, s2
	s_addk_i32 s8, 0x7000
	s_waitcnt vmcnt(0)
	s_waitcnt vmcnt(0) lgkmcnt(0)
	s_barrier
	ds_read_b128 v[32:35], v177
	ds_read_b128 v[54:57], v177 offset:2048
	ds_read_b128 v[66:69], v176
	ds_read_b128 v[76:79], v176 offset:2048
	global_load_lds_dwordx4 v[58:59], off
	v_lshl_add_u64 v[58:59], s[48:49], 0, v[60:61]
	v_add_u32_e32 v60, s8, v170
	s_waitcnt lgkmcnt(0)
	v_mfma_f32_32x32x16_bf16 v[32:47], v[32:35], v[132:135], 0
	v_readfirstlane_b32 s2, v60
	v_add_u32_e32 v60, s8, v171
	s_mov_b32 m0, s2
	v_readfirstlane_b32 s2, v60
	global_load_lds_dwordx4 v[58:59], off
	v_lshl_add_u64 v[58:59], s[48:49], 0, v[62:63]
	s_mov_b32 m0, s2
	v_pk_add_f32 v[48:49], v[48:49], 0 op_sel_hi:[1,0]
	global_load_lds_dwordx4 v[58:59], off
	v_pk_add_f32 v[48:49], v[52:53], v[48:49]
	v_mfma_f32_32x32x16_bf16 v[32:47], v[66:69], v[128:131], v[32:47]
	v_add_f32_e64 v70, v50, v48
	v_add_f32_e64 v71, v51, v49
	v_add_f32_e64 v80, v100, 0
	v_add_f32_e64 v81, v101, 0
	v_add_f32_e64 v70, v154, v70
	v_add_f32_e64 v71, v155, v71
	v_pk_add_f32 v[80:81], v[102:103], v[80:81]
	v_pk_add_f32 v[70:71], v[152:153], v[70:71]
	v_pk_add_f32 v[80:81], v[104:105], v[80:81]
	v_pk_add_f32 v[66:67], v[126:127], v[70:71]
	v_mfma_f32_32x32x16_bf16 v[48:63], v[54:57], v[132:135], 0
	v_add_f32_e64 v66, v124, v66
	v_add_f32_e64 v67, v125, v67
	v_add_f32_e64 v80, v106, v80
	v_add_f32_e64 v81, v107, v81
	v_add_f32_e64 v66, v110, v66
	v_add_f32_e64 v67, v111, v67
	v_pk_add_f32 v[80:81], v[108:109], v[80:81]
	v_pk_add_f32 v[66:67], v[168:169], v[66:67]
	s_nop 0
	v_pk_add_f32 v[66:67], v[166:167], v[66:67]
	v_mfma_f32_32x32x16_bf16 v[48:63], v[76:79], v[128:131], v[48:63]
	v_add_f32_e64 v70, v164, v66
	v_add_f32_e64 v71, v165, v67
	ds_read_b128 v[66:69], v177 offset:12288
	v_add_f32_e64 v76, v96, v80
	v_add_f32_e64 v77, v97, v81
	v_pk_add_f32 v[70:71], v[158:159], v[70:71]
	v_pk_add_f32 v[80:81], v[98:99], v[76:77]
	ds_read_b128 v[76:79], v177 offset:14336
	v_pk_add_f32 v[70:71], v[156:157], v[70:71]
	s_waitcnt lgkmcnt(0)
	v_mfma_f32_32x32x16_bf16 v[96:111], v[66:69], v[132:135], 0
	v_add_f32_e64 v66, v112, v80
	v_add_f32_e64 v67, v113, v81
	v_add_f32_e64 v70, v162, v70
	v_add_f32_e64 v71, v163, v71
	v_add_f32_e64 v66, v122, v66
	v_add_f32_e64 v67, v123, v67
	v_pk_add_f32 v[70:71], v[160:161], v[70:71]
	v_pk_add_f32 v[66:67], v[120:121], v[66:67]
	v_pk_add_f32 v[70:71], v[150:151], v[70:71]
	v_pk_add_f32 v[66:67], v[118:119], v[66:67]
	s_nop 0
	v_pk_add_f32 v[66:67], v[116:117], v[66:67]
	s_nop 0
	v_pk_add_f32 v[80:81], v[114:115], v[66:67]
	ds_read_b128 v[66:69], v176 offset:12288
	s_waitcnt lgkmcnt(0)
	v_mfma_f32_32x32x16_bf16 v[96:111], v[66:69], v[128:131], v[96:111]
	v_max_f32_e32 v66, v63, v63
	v_max_f32_e32 v67, v47, v47
	v_max_f32_e32 v66, v67, v66
	v_max3_f32 v67, v66, v32, v33
	v_max3_f32 v66, v66, v48, v49
	s_nop 0
	v_max3_f32 v66, v66, v50, v51
	v_mfma_f32_32x32x16_bf16 v[112:127], v[76:79], v[132:135], 0
	v_add_f32_e64 v76, v148, v80
	v_add_f32_e64 v77, v149, v81
	v_max3_f32 v67, v67, v34, v35
	v_max3_f32 v66, v66, v52, v53
	v_add_f32_e64 v76, v146, v76
	v_add_f32_e64 v77, v147, v77
	v_max3_f32 v67, v67, v36, v37
	v_max3_f32 v66, v66, v54, v55
	v_add_f32_e64 v76, v144, v76
	v_add_f32_e64 v77, v145, v77
	v_max3_f32 v67, v67, v38, v39
	v_max3_f32 v66, v66, v56, v57
	v_pk_add_f32 v[70:71], v[70:71], v[76:77]
	ds_read_b128 v[76:79], v176 offset:14336
	v_max3_f32 v67, v67, v40, v41
	v_max3_f32 v66, v66, v58, v59
	s_waitcnt lgkmcnt(0)
	v_mfma_f32_32x32x16_bf16 v[112:127], v[76:79], v[128:131], v[112:127]
	v_max3_f32 v67, v67, v42, v43
	v_max3_f32 v66, v66, v60, v61
	v_add_f32_e32 v65, v175, v71
	v_max3_f32 v67, v67, v44, v45
	v_add_f32_e32 v145, v70, v65
	v_max3_f32 v66, v67, v66, v46
	ds_bpermute_b32 v148, v178, v145
	v_max3_f32 v66, v66, v62, v66
	ds_bpermute_b32 v67, v178, v66
	v_max_f32_e32 v65, v66, v66
	s_waitcnt lgkmcnt(0)
	v_max_f32_e32 v66, v67, v67
	v_max_f32_e32 v65, v65, v66
	v_cmp_gt_f32_e64 vcc, |v65|, s7
	s_cmp_lg_u64 vcc, 0
	s_cselect_b64 s[28:29], -1, 0
	s_cmp_eq_u64 vcc, 0
	s_cselect_b64 s[46:47], -1, 0
	s_cbranch_vccz .LBB0_184
	v_cndmask_b32_e32 v144, 0, v65, vcc
	v_pk_add_f32 v[32:33], v[32:33], v[144:145] op_sel_hi:[1,0] neg_lo:[0,1] neg_hi:[0,1]
	v_pk_add_f32 v[48:49], v[48:49], v[144:145] op_sel_hi:[1,0] neg_lo:[0,1] neg_hi:[0,1]
	v_pk_add_f32 v[34:35], v[34:35], v[144:145] op_sel_hi:[1,0] neg_lo:[0,1] neg_hi:[0,1]
	v_pk_add_f32 v[50:51], v[50:51], v[144:145] op_sel_hi:[1,0] neg_lo:[0,1] neg_hi:[0,1]
	v_pk_add_f32 v[36:37], v[36:37], v[144:145] op_sel_hi:[1,0] neg_lo:[0,1] neg_hi:[0,1]
	v_pk_add_f32 v[52:53], v[52:53], v[144:145] op_sel_hi:[1,0] neg_lo:[0,1] neg_hi:[0,1]
	v_pk_add_f32 v[38:39], v[38:39], v[144:145] op_sel_hi:[1,0] neg_lo:[0,1] neg_hi:[0,1]
	v_pk_add_f32 v[54:55], v[54:55], v[144:145] op_sel_hi:[1,0] neg_lo:[0,1] neg_hi:[0,1]
	v_pk_add_f32 v[40:41], v[40:41], v[144:145] op_sel_hi:[1,0] neg_lo:[0,1] neg_hi:[0,1]
	v_pk_add_f32 v[56:57], v[56:57], v[144:145] op_sel_hi:[1,0] neg_lo:[0,1] neg_hi:[0,1]
	v_pk_add_f32 v[42:43], v[42:43], v[144:145] op_sel_hi:[1,0] neg_lo:[0,1] neg_hi:[0,1]
	v_pk_add_f32 v[58:59], v[58:59], v[144:145] op_sel_hi:[1,0] neg_lo:[0,1] neg_hi:[0,1]
	v_pk_add_f32 v[44:45], v[44:45], v[144:145] op_sel_hi:[1,0] neg_lo:[0,1] neg_hi:[0,1]
	v_pk_add_f32 v[60:61], v[60:61], v[144:145] op_sel_hi:[1,0] neg_lo:[0,1] neg_hi:[0,1]
	v_pk_add_f32 v[46:47], v[46:47], v[144:145] op_sel_hi:[1,0] neg_lo:[0,1] neg_hi:[0,1]
	v_pk_add_f32 v[62:63], v[62:63], v[144:145] op_sel_hi:[1,0] neg_lo:[0,1] neg_hi:[0,1]
	v_sub_f32_e32 v111, v111, v144
	v_sub_f32_e32 v110, v110, v144
	v_sub_f32_e32 v109, v109, v144
	v_sub_f32_e32 v108, v108, v144
	v_sub_f32_e32 v107, v107, v144
	v_sub_f32_e32 v106, v106, v144
	v_sub_f32_e32 v105, v105, v144
	v_sub_f32_e32 v104, v104, v144
	v_sub_f32_e32 v103, v103, v144
	v_sub_f32_e32 v102, v102, v144
	v_sub_f32_e32 v101, v101, v144
	v_sub_f32_e32 v100, v100, v144
	v_sub_f32_e32 v99, v99, v144
	v_sub_f32_e32 v98, v98, v144
	v_sub_f32_e32 v97, v97, v144
	v_sub_f32_e32 v96, v96, v144
	v_sub_f32_e32 v127, v127, v144
	v_sub_f32_e32 v126, v126, v144
	v_sub_f32_e32 v125, v125, v144
	v_sub_f32_e32 v124, v124, v144
	v_sub_f32_e32 v123, v123, v144
	v_sub_f32_e32 v122, v122, v144
	v_sub_f32_e32 v121, v121, v144
	v_sub_f32_e32 v120, v120, v144
	v_sub_f32_e32 v119, v119, v144
	v_sub_f32_e32 v118, v118, v144
	v_sub_f32_e32 v117, v117, v144
	v_sub_f32_e32 v116, v116, v144
	v_sub_f32_e32 v115, v115, v144
	v_sub_f32_e32 v114, v114, v144
	v_sub_f32_e32 v113, v113, v144
	v_sub_f32_e32 v112, v112, v144
	s_branch .LBB0_185

.LBB0_214:
	s_lshl_b32 s2, s97, 2
	s_add_i32 s8, s2, s96
	v_mad_i64_i32 v[0:1], s[2:3], s8, v232, v[138:139]
	v_mov_b64_e32 v[2:3], s[78:79]
	s_movk_i32 s5, 0xc0
	v_mov_b32_e32 v5, v220
	v_mad_u64_u32 v[2:3], s[2:3], v0, s5, v[2:3]
	v_mad_i32_i24 v3, v1, s5, v3
	v_and_b32_e32 v34, 31, v5
	v_lshlrev_b32_e32 v0, 1, v5
	v_and_b32_e32 v6, 8, v0
	v_mul_u32_u24_e32 v0, 0x60, v34
	v_bfe_u32 v33, v5, 5, 1
	v_lshlrev_b32_e32 v192, 1, v0
	v_lshl_add_u64 v[0:1], v[2:3], 0, v[192:193]
	v_lshlrev_b32_e32 v192, 4, v33
	v_lshl_add_u64 v[0:1], v[0:1], 0, v[192:193]
	global_load_dwordx4 v[116:119], v[0:1], off nt
	global_load_dwordx4 v[112:115], v[0:1], off offset:32 nt
	global_load_dwordx4 v[108:111], v[0:1], off offset:64 nt
	v_ashrrev_i32_e32 v8, 6, v5
	v_bfe_u32 v4, v5, 3, 3
	v_lshl_or_b32 v9, v8, 3, v4
	s_mul_i32 s3, s8, 0x18c000
	global_load_dwordx4 v[104:107], v[0:1], off offset:96 nt
	global_load_dwordx4 v[100:103], v[0:1], off offset:128 nt
	global_load_dwordx4 v[96:99], v[0:1], off offset:160 nt
	v_lshrrev_b32_e32 v0, 1, v9
	s_mul_hi_i32 s2, s8, 0x18c000
	s_add_u32 s5, s80, s3
	v_xor_b32_e32 v0, v0, v5
	s_addc_u32 s11, s81, s2
	s_mul_hi_i32 s2, s8, 0x108000
	s_mul_i32 s8, s8, 0x108000
	v_lshlrev_b32_e32 v0, 3, v0
	s_add_u32 s12, s82, s8
	v_and_b32_e32 v1, 19, v5
	v_and_b32_e32 v0, 56, v0
	s_addc_u32 s16, s83, s2
	v_mad_u64_u32 v[2:3], s[2:3], v9, s65, v[0:1]
	v_add_u32_e32 v3, 4, v8
	v_lshl_or_b32 v10, v3, 3, v4
	v_lshrrev_b32_e32 v4, 1, v10
	v_xor_b32_e32 v4, v4, v5
	v_lshlrev_b32_e32 v4, 3, v4
	v_and_b32_e32 v4, 56, v4
	v_mad_u64_u32 v[120:121], s[2:3], v10, s65, v[4:5]
	v_lshlrev_b32_e32 v130, 10, v3
	v_bfe_u32 v3, v5, 2, 4
	s_mul_i32 s2, s13, 0x3000
	v_lshlrev_b32_e32 v129, 10, v8
	v_lshl_or_b32 v3, v8, 4, v3
	v_lshrrev_b32_e32 v8, 4, v5
	s_add_u32 s18, s5, s2
	v_lshrrev_b32_e32 v32, 1, v5
	v_xor_b32_e32 v5, v8, v5
	s_addc_u32 s19, s11, 0
	v_mul_lo_u32 v3, v3, s65
	v_lshlrev_b32_e32 v5, 3, v5
	s_cmp_lg_u32 32, -1
	v_and_or_b32 v3, v5, 24, v3
	s_cselect_b32 s2, 32, 0
	v_add_u32_e32 v122, 64, v3
	v_mul_lo_u32 v3, v9, s4
	v_mov_b32_e32 v192, v2
	v_add_u32_e32 v2, s2, v129
	v_and_b32_e32 v7, 4, v32
	v_or_b32_e32 v124, v0, v3
	v_mul_lo_u32 v0, v10, s4
	v_lshlrev_b64 v[46:47], 1, v[192:193]
	v_readfirstlane_b32 s3, v2
	v_add_u32_e32 v2, s2, v130
	v_or_b32_e32 v126, v4, v0
	v_or3_b32 v6, v6, v1, v7
	v_lshl_add_u64 v[0:1], s[18:19], 0, v[46:47]
	s_mov_b32 m0, s3
	v_readfirstlane_b32 s3, v2
	global_load_lds_dwordx4 v[0:1], off
	v_mov_b32_e32 v121, v193
	s_mov_b32 m0, s3
	s_add_i32 s3, s2, 0x2000
	v_lshlrev_b64 v[48:49], 1, v[120:121]
	v_add_u32_e32 v2, s3, v129
	v_lshl_add_u64 v[0:1], s[18:19], 0, v[48:49]
	v_readfirstlane_b32 s3, v2
	global_load_lds_dwordx4 v[0:1], off
	s_mov_b32 m0, s3
	s_lshl_b32 s3, s13, 7
	s_add_u32 s28, s12, s3
	v_mov_b32_e32 v123, v193
	s_addc_u32 s29, s16, 0
	s_add_i32 s3, s2, 0x3000
	v_lshlrev_b64 v[50:51], 1, v[122:123]
	v_mov_b32_e32 v125, v193
	v_add_u32_e32 v2, s3, v129
	v_lshl_add_u64 v[0:1], s[18:19], 0, v[50:51]
	v_lshlrev_b64 v[52:53], 1, v[124:125]
	v_readfirstlane_b32 s8, v2
	v_add_u32_e32 v4, s3, v130
	global_load_lds_dwordx4 v[0:1], off
	v_lshl_add_u64 v[0:1], s[28:29], 0, v[52:53]
	s_mov_b32 m0, s8
	v_readfirstlane_b32 s3, v4
	s_add_u32 s18, s18, 0x3000
	global_load_lds_dwordx4 v[0:1], off
	v_mov_b32_e32 v127, v193
	s_mov_b32 m0, s3
	s_addc_u32 s19, s19, 0
	s_add_i32 s3, s2, 0x5000
	v_lshlrev_b64 v[54:55], 1, v[126:127]
	v_add_u32_e32 v7, s3, v129
	v_lshl_add_u64 v[2:3], s[28:29], 0, v[54:55]
	v_readfirstlane_b32 s8, v7
	v_add_u32_e32 v7, s3, v130
	global_load_lds_dwordx4 v[2:3], off
	v_lshl_add_u64 v[4:5], s[18:19], 0, v[46:47]
	s_mov_b32 m0, s8
	v_readfirstlane_b32 s3, v7
	global_load_lds_dwordx4 v[4:5], off
	s_mov_b32 m0, s3
	s_add_i32 s3, s2, 0x7000
	v_add_u32_e32 v7, s3, v129
	v_lshl_add_u64 v[4:5], s[18:19], 0, v[48:49]
	v_readfirstlane_b32 s3, v7
	global_load_lds_dwordx4 v[4:5], off
	v_lshl_add_u64 v[4:5], s[18:19], 0, v[50:51]
	s_mov_b32 m0, s3
	s_add_i32 s3, s2, 0x8000
	global_load_lds_dwordx4 v[4:5], off
	v_add_u32_e32 v4, s3, v129
	v_lshl_add_u64 v[0:1], v[0:1], 0, s[36:37]
	v_readfirstlane_b32 s8, v4
	s_mov_b32 m0, s8
	v_lshrrev_b32_e32 v56, 1, v6
	global_load_lds_dwordx4 v[0:1], off
	v_lshl_add_u64 v[0:1], v[2:3], 0, s[36:37]
	v_add_u32_e32 v2, s3, v130
	v_lshlrev_b32_e32 v132, 7, v6
	v_readfirstlane_b32 s3, v2
	s_mov_b32 m0, s3
	v_or_b32_e32 v35, 2, v33
	global_load_lds_dwordx4 v[0:1], off
	v_bitop3_b32 v0, v56, v33, 7 bitop3:0x6c
	v_lshlrev_b32_e32 v133, 4, v0
	v_add_u32_e32 v0, 32, v133
	v_add_u32_e32 v142, v0, v132
	s_waitcnt vmcnt(0)
	s_waitcnt vmcnt(0) lgkmcnt(0)
	s_barrier
	ds_read_b128 v[0:3], v142
	v_bitop3_b32 v36, v56, v35, 7 bitop3:0x6c
	ds_read_b128 v[16:19], v142 offset:4096
	v_lshlrev_b32_e32 v134, 4, v36
	v_add_u32_e32 v36, 32, v134
	v_add_u32_e32 v143, v36, v132
	ds_read_b128 v[36:39], v143
	v_lshrrev_b32_e32 v57, 2, v6
	v_lshlrev_b32_e32 v131, 6, v6
	ds_read_b128 v[40:43], v143 offset:4096
	s_waitcnt lgkmcnt(3)
	v_mfma_f32_32x32x16_bf16 v[0:15], v[0:3], v[116:119], 0
	s_or_b32 s3, s13, 2
	s_mul_i32 s8, s3, 0x3000
	s_add_u32 s18, s5, s8
	s_addc_u32 s19, s11, 0
	s_add_i32 s8, s2, 0xa000
	s_lshl_b32 s3, s3, 7
	v_cmp_lt_i32_e32 vcc, v225, v224
	s_waitcnt lgkmcnt(2)
	v_mfma_f32_32x32x16_bf16 v[16:31], v[16:19], v[116:119], 0
	s_waitcnt lgkmcnt(1)
	v_mfma_f32_32x32x16_bf16 v[0:15], v[36:39], v[112:115], v[0:15]
	v_or_b32_e32 v36, 4, v33
	v_bitop3_b32 v37, v56, v36, 7 bitop3:0x6c
	v_lshlrev_b32_e32 v135, 4, v37
	v_add_u32_e32 v37, 32, v135
	v_add_u32_e32 v149, v37, v132
	v_or_b32_e32 v37, 6, v33
	s_waitcnt lgkmcnt(0)
	v_mfma_f32_32x32x16_bf16 v[16:31], v[40:43], v[112:115], v[16:31]
	ds_read_b128 v[38:41], v149
	ds_read_b128 v[42:45], v149 offset:4096
	s_waitcnt lgkmcnt(1)
	v_mfma_f32_32x32x16_bf16 v[0:15], v[38:41], v[108:111], v[0:15]
	v_bitop3_b32 v38, v56, v37, 7 bitop3:0x6c
	v_lshlrev_b32_e32 v138, 4, v38
	v_add_u32_e32 v38, 32, v138
	v_add_u32_e32 v150, v38, v132
	ds_read_b128 v[38:41], v150
	v_add_u32_e32 v56, 32, v131
	s_waitcnt lgkmcnt(0)
	v_mfma_f32_32x32x16_bf16 v[0:15], v[38:41], v[104:107], v[0:15]
	v_bitop3_b32 v38, v57, v33, 3 bitop3:0x6c
	v_lshlrev_b32_e32 v140, 4, v38
	v_add_u32_e32 v151, v56, v140
	ds_read_b128 v[38:41], v151 offset:8192
	s_waitcnt lgkmcnt(0)
	v_mfma_f32_32x32x16_bf16 v[0:15], v[38:41], v[100:103], v[0:15]
	v_bitop3_b32 v38, v57, v35, 3 bitop3:0x6c
	v_lshlrev_b32_e32 v141, 4, v38
	v_add_u32_e32 v152, v56, v141
	ds_read_b128 v[38:41], v152 offset:8192
	v_mfma_f32_32x32x16_bf16 v[16:31], v[42:45], v[108:111], v[16:31]
	ds_read_b128 v[42:45], v150 offset:4096
	s_waitcnt lgkmcnt(0)
	v_mfma_f32_32x32x16_bf16 v[16:31], v[42:45], v[104:107], v[16:31]
	ds_read_b128 v[42:45], v151 offset:10240
	s_waitcnt lgkmcnt(0)
	v_mfma_f32_32x32x16_bf16 v[16:31], v[42:45], v[100:103], v[16:31]
	ds_read_b128 v[42:45], v152 offset:10240
	v_mfma_f32_32x32x16_bf16 v[0:15], v[38:41], v[96:99], v[0:15]
	v_add_u32_e32 v40, s8, v129
	v_lshl_add_u64 v[38:39], s[18:19], 0, v[46:47]
	v_readfirstlane_b32 s10, v40
	v_add_u32_e32 v40, s8, v130
	s_mov_b32 m0, s10
	v_readfirstlane_b32 s8, v40
	global_load_lds_dwordx4 v[38:39], off
	v_lshl_add_u64 v[38:39], s[18:19], 0, v[48:49]
	s_mov_b32 m0, s8
	s_add_i32 s8, s2, 0xc000
	global_load_lds_dwordx4 v[38:39], off
	v_lshl_add_u64 v[38:39], s[18:19], 0, v[50:51]
	s_add_u32 s18, s12, s3
	v_add_u32_e32 v40, s8, v129
	s_addc_u32 s19, s16, 0
	s_add_i32 s2, s2, 0xd000
	v_readfirstlane_b32 s8, v40
	v_add_u32_e32 v40, s2, v129
	s_mov_b32 m0, s8
	v_readfirstlane_b32 s3, v40
	v_add_u32_e32 v40, s2, v130
	global_load_lds_dwordx4 v[38:39], off
	v_lshl_add_u64 v[38:39], s[18:19], 0, v[52:53]
	s_mov_b32 m0, s3
	v_readfirstlane_b32 s2, v40
	global_load_lds_dwordx4 v[38:39], off
	v_lshl_add_u64 v[38:39], s[18:19], 0, v[54:55]
	s_mov_b32 m0, s2
	s_waitcnt lgkmcnt(0)
	v_mfma_f32_32x32x16_bf16 v[16:31], v[42:45], v[96:99], v[16:31]
	global_load_lds_dwordx4 v[38:39], off
	ds_read_b128 v[38:41], v142 offset:20480
	ds_read_b128 v[42:45], v142 offset:24576
	s_waitcnt lgkmcnt(0)
	v_mfma_f32_32x32x16_bf16 v[64:79], v[38:41], v[116:119], 0
	ds_read_b128 v[38:41], v143 offset:20480
	s_waitcnt lgkmcnt(0)
	v_mfma_f32_32x32x16_bf16 v[64:79], v[38:41], v[112:115], v[64:79]
	ds_read_b128 v[38:41], v149 offset:20480
	v_mfma_f32_32x32x16_bf16 v[80:95], v[42:45], v[116:119], 0
	ds_read_b128 v[42:45], v143 offset:24576
	s_waitcnt lgkmcnt(0)
	v_mfma_f32_32x32x16_bf16 v[64:79], v[38:41], v[108:111], v[64:79]
	ds_read_b128 v[38:41], v150 offset:20480
	v_mfma_f32_32x32x16_bf16 v[80:95], v[42:45], v[112:115], v[80:95]
	ds_read_b128 v[42:45], v149 offset:24576
	s_waitcnt lgkmcnt(0)
	v_mfma_f32_32x32x16_bf16 v[64:79], v[38:41], v[104:107], v[64:79]
	ds_read_b128 v[38:41], v151 offset:28672
	v_mfma_f32_32x32x16_bf16 v[80:95], v[42:45], v[108:111], v[80:95]
	ds_read_b128 v[42:45], v150 offset:24576
	s_waitcnt lgkmcnt(0)
	v_mfma_f32_32x32x16_bf16 v[64:79], v[38:41], v[100:103], v[64:79]
	ds_read_b128 v[38:41], v152 offset:28672
	v_mfma_f32_32x32x16_bf16 v[80:95], v[42:45], v[104:107], v[80:95]
	ds_read_b128 v[42:45], v151 offset:30720
	s_waitcnt lgkmcnt(0)
	v_mfma_f32_32x32x16_bf16 v[64:79], v[38:41], v[96:99], v[64:79]
	v_max_f32_e32 v38, v31, v31
	v_max_f32_e32 v39, v15, v15
	v_max_f32_e32 v38, v39, v38
	v_max3_f32 v39, v38, v0, v1
	v_max3_f32 v38, v38, v16, v17
	s_nop 0
	v_max3_f32 v39, v39, v2, v3
	v_max3_f32 v38, v38, v18, v19
	v_mfma_f32_32x32x16_bf16 v[80:95], v[42:45], v[100:103], v[80:95]
	v_max3_f32 v39, v39, v4, v5
	v_max3_f32 v38, v38, v20, v21
	ds_read_b128 v[42:45], v152 offset:30720
	v_max3_f32 v39, v39, v6, v7
	v_max3_f32 v38, v38, v22, v23
	s_nop 0
	v_max3_f32 v39, v39, v8, v9
	v_max3_f32 v38, v38, v24, v25
	s_waitcnt lgkmcnt(0)
	v_mfma_f32_32x32x16_bf16 v[80:95], v[42:45], v[96:99], v[80:95]
	v_max3_f32 v39, v39, v10, v11
	v_max3_f32 v38, v38, v26, v27
	s_nop 0
	v_max3_f32 v39, v39, v12, v13
	v_max3_f32 v38, v38, v28, v29
	s_nop 0
	v_max3_f32 v38, v39, v38, v14
	v_cndmask_b32_e32 v39, v223, v225, vcc
	v_lshlrev_b32_e32 v144, 2, v39
	v_max3_f32 v38, v38, v30, v38
	ds_bpermute_b32 v39, v144, v38
	v_max_f32_e32 v38, v38, v38
	s_waitcnt lgkmcnt(0)
	v_max_f32_e32 v39, v39, v39
	v_max_f32_e32 v38, v38, v39
	v_cmp_gt_f32_e64 vcc, |v38|, s7
	s_cmp_lg_u64 vcc, 0
	s_cselect_b64 s[28:29], -1, 0
	s_cmp_eq_u64 vcc, 0
	s_cselect_b64 s[42:43], -1, 0
	s_cbranch_vccz .LBB0_216
	v_cndmask_b32_e32 v128, 0, v38, vcc
	v_pk_add_f32 v[0:1], v[0:1], v[128:129] op_sel_hi:[1,0] neg_lo:[0,1] neg_hi:[0,1]
	v_pk_add_f32 v[16:17], v[16:17], v[128:129] op_sel_hi:[1,0] neg_lo:[0,1] neg_hi:[0,1]
	v_pk_add_f32 v[2:3], v[2:3], v[128:129] op_sel_hi:[1,0] neg_lo:[0,1] neg_hi:[0,1]
	v_pk_add_f32 v[18:19], v[18:19], v[128:129] op_sel_hi:[1,0] neg_lo:[0,1] neg_hi:[0,1]
	v_pk_add_f32 v[4:5], v[4:5], v[128:129] op_sel_hi:[1,0] neg_lo:[0,1] neg_hi:[0,1]
	v_pk_add_f32 v[20:21], v[20:21], v[128:129] op_sel_hi:[1,0] neg_lo:[0,1] neg_hi:[0,1]
	v_pk_add_f32 v[6:7], v[6:7], v[128:129] op_sel_hi:[1,0] neg_lo:[0,1] neg_hi:[0,1]
	v_pk_add_f32 v[22:23], v[22:23], v[128:129] op_sel_hi:[1,0] neg_lo:[0,1] neg_hi:[0,1]
	v_pk_add_f32 v[8:9], v[8:9], v[128:129] op_sel_hi:[1,0] neg_lo:[0,1] neg_hi:[0,1]
	v_pk_add_f32 v[24:25], v[24:25], v[128:129] op_sel_hi:[1,0] neg_lo:[0,1] neg_hi:[0,1]
	v_pk_add_f32 v[10:11], v[10:11], v[128:129] op_sel_hi:[1,0] neg_lo:[0,1] neg_hi:[0,1]
	v_pk_add_f32 v[26:27], v[26:27], v[128:129] op_sel_hi:[1,0] neg_lo:[0,1] neg_hi:[0,1]
	v_pk_add_f32 v[12:13], v[12:13], v[128:129] op_sel_hi:[1,0] neg_lo:[0,1] neg_hi:[0,1]
	v_pk_add_f32 v[28:29], v[28:29], v[128:129] op_sel_hi:[1,0] neg_lo:[0,1] neg_hi:[0,1]
	v_pk_add_f32 v[14:15], v[14:15], v[128:129] op_sel_hi:[1,0] neg_lo:[0,1] neg_hi:[0,1]
	v_pk_add_f32 v[30:31], v[30:31], v[128:129] op_sel_hi:[1,0] neg_lo:[0,1] neg_hi:[0,1]
	v_sub_f32_e32 v79, v79, v128
	v_sub_f32_e32 v78, v78, v128
	v_sub_f32_e32 v77, v77, v128
	v_sub_f32_e32 v76, v76, v128
	v_sub_f32_e32 v75, v75, v128
	v_sub_f32_e32 v74, v74, v128
	v_sub_f32_e32 v73, v73, v128
	v_sub_f32_e32 v72, v72, v128
	v_sub_f32_e32 v71, v71, v128
	v_sub_f32_e32 v70, v70, v128
	v_sub_f32_e32 v69, v69, v128
	v_sub_f32_e32 v68, v68, v128
	v_sub_f32_e32 v67, v67, v128
	v_sub_f32_e32 v66, v66, v128
	v_sub_f32_e32 v65, v65, v128
	v_sub_f32_e32 v64, v64, v128
	v_sub_f32_e32 v95, v95, v128
	v_sub_f32_e32 v94, v94, v128
	v_sub_f32_e32 v93, v93, v128
	v_sub_f32_e32 v92, v92, v128
	v_sub_f32_e32 v91, v91, v128
	v_sub_f32_e32 v90, v90, v128
	v_sub_f32_e32 v89, v89, v128
	v_sub_f32_e32 v88, v88, v128
	v_sub_f32_e32 v87, v87, v128
	v_sub_f32_e32 v86, v86, v128
	v_sub_f32_e32 v85, v85, v128
	v_sub_f32_e32 v84, v84, v128
	v_sub_f32_e32 v83, v83, v128
	v_sub_f32_e32 v82, v82, v128
	v_sub_f32_e32 v81, v81, v128
	v_sub_f32_e32 v80, v80, v128
	s_branch .LBB0_217
